# attention A phase start: early vmcnt(0) behind the softmax-shift constant load removed (covered by the bias-table loop's wait); on top of v84
# baseline (speedup 1.0000x reference)
; #define LAS __attribute__((address_space(3)))
; __device__ __forceinline__ int lane_id() { int l; asm volatile("v_mbcnt_lo_u32_b32 %0, -1, 0\n\tv_mbcnt_hi_u32_b32 %0, -1, %0" : "=v"(l)); return l; }
; __device__ __forceinline__ void attn_a_phase(Frame& F, const float cshift, const bf16* qkv, const bf16* gate, bf16* y, const float* t5, const float* qg, const float* kg) {
;     LAS char* lds = (LAS char*)F.lds;
;     LAS float* scr = (LAS float*)(lds + SCR_OFF);
;     int tid_ = F.wave * 64 + lane_id(); asm volatile("" : "+v"(tid_));
;     const int tid = tid_, lane = tid & 63, wave = __builtin_amdgcn_readfirstlane(tid >> 6);
;     const int NU = BCH * NH * 8, per = (NU + F.G - 1) / F.G, u0 = F.vcu * per, nu = min(per, NU - u0);
;     if (nu <= 0) return;
;     const float zero16[16] = {0.f, 0.f, 0.f, 0.f, 0.f, 0.f, 0.f, 0.f, 0.f, 0.f, 0.f, 0.f, 0.f, 0.f, 0.f, 0.f};
;     LAS char* stage = lds + VST_OFF + wave * STAGE_BYTES;
;     Lay L; lay_init(L, lane);
;     Seg cur; St st;
;     seg_a(cur, u0, 0, 0, qkv, lds, lane, wave); seg_start(cur, st, lane); dma_tile(cur.kt, cur.vt, stage, L);
;     tbl_a(u0, 0, t5, cshift, lds, tid);
.LBB0_302:
	s_andn2_b64 vcc, exec, s[18:19]
	s_cbranch_vccnz .LBB0_189
	v_readlane_b32 s12, v253, 20
	v_readlane_b32 s13, v253, 21
	s_waitcnt lgkmcnt(0)
	s_nop 3
	global_load_dword v153, v161, s[12:13]
	v_readlane_b32 s12, v252, 21
	v_mbcnt_lo_u32_b32 v0, -1, 0
	v_mbcnt_hi_u32_b32 v0, -1, v0
	v_readlane_b32 s13, v252, 22
	v_add_u32_e32 v158, s65, v0
	s_andn2_b64 vcc, exec, s[12:13]
	v_readfirstlane_b32 s2, v158
	s_cbranch_vccnz .LBB0_367
	v_bfe_u32 v1, v158, 4, 1
	v_bfe_u32 v3, v158, 5, 1
	v_lshlrev_b32_e32 v0, 7, v158
	v_and_b32_e32 v0, 0x400, v0
	v_lshlrev_b32_e32 v2, 9, v3
	v_lshlrev_b32_e32 v4, 8, v1
	s_ashr_i32 s2, s2, 6
	v_and_b32_e32 v6, 7, v158
	v_or3_b32 v0, v0, v2, v4
	v_lshlrev_b32_e32 v2, 2, v3
	v_lshlrev_b32_e32 v4, 1, v1
	s_lshl_b32 s12, s2, 13
	v_or_b32_e32 v5, v4, v2
	v_bitop3_b32 v2, v4, v6, v2 bitop3:0x36
	v_and_b32_e32 v7, 3, v158
	s_add_i32 s14, s12, 0
	v_lshl_or_b32 v144, v2, 4, v0
	v_bitop3_b32 v2, v5, v6, 1 bitop3:0x36
	v_lshlrev_b32_e32 v4, 5, v158
	v_lshlrev_b32_e32 v5, 4, v7
	s_movk_i32 s12, 0x780
	v_and_or_b32 v146, v4, s12, v5
	s_lshl_b32 s64, s2, 9
	v_readlane_b32 s12, v252, 23
	v_and_b32_e32 v159, 31, v158
	s_or_b32 s12, s12, s64
	v_or_b32_e32 v4, s12, v159
	v_readlane_b32 s13, v252, 25
	v_ashrrev_i32_e32 v5, 31, v4
	v_readlane_b32 s18, v252, 29
	s_add_i32 s12, s12, s13
	v_lshlrev_b64 v[4:5], 7, v[4:5]
	v_readlane_b32 s19, v252, 30
	s_ashr_i32 s13, s12, 31
	s_add_i32 s63, s14, 0x13900
	v_lshl_add_u64 v[150:151], s[18:19], 0, v[4:5]
	s_lshl_b64 s[12:13], s[12:13], 7
	v_readlane_b32 s15, v252, 26
	v_lshrrev_b32_e32 v4, 2, v158
	s_add_u32 s18, s15, s12
	v_readlane_b32 s15, v252, 27
	v_and_b32_e32 v8, 8, v4
	s_addc_u32 s19, s15, s13
	v_readlane_b32 s15, v252, 28
	v_lshlrev_b32_e32 v160, 1, v8
	v_lshl_add_u32 v148, v2, 4, v0
	v_mov_b32_e32 v149, v161
	s_add_u32 s20, s15, s12
	v_readlane_b32 s12, v252, 31
	v_lshl_add_u64 v[4:5], v[150:151], 0, v[160:161]
	v_mov_b32_e32 v145, v161
	s_mov_b32 m0, s63
	v_lshl_add_u64 v[12:13], s[18:19], 0, v[148:149]
	s_addc_u32 s21, s12, s13
	global_load_dwordx4 v[80:83], v[4:5], off
	global_load_dwordx4 v[84:87], v[4:5], off offset:32
	global_load_dwordx4 v[88:91], v[4:5], off offset:64
	global_load_dwordx4 v[92:95], v[4:5], off offset:96
	v_lshl_add_u64 v[10:11], s[18:19], 0, v[144:145]
	global_load_lds_dwordx4 v144, s[18:19]
	v_lshl_add_u64 v[14:15], v[12:13], 0, s[4:5]
	s_add_i32 m0, s14, 0x13d00
	v_lshl_add_u64 v[10:11], v[10:11], 0, s[6:7]
	global_load_lds_dwordx4 v[14:15], off
	s_add_i32 m0, s14, 0x14100
	v_mov_b32_e32 v147, v161
	global_load_lds_dwordx4 v[10:11], off
	v_lshl_add_u64 v[10:11], v[12:13], 0, s[8:9]
	s_add_i32 m0, s14, 0x14500
	v_lshl_add_u64 v[4:5], s[20:21], 0, v[146:147]
	global_load_lds_dwordx4 v[10:11], off
	s_add_i32 m0, s14, 0x14900
	v_lshl_add_u64 v[10:11], v[4:5], 0, s[6:7]
	global_load_lds_dwordx4 v146, s[20:21]
	s_add_i32 m0, s14, 0x14d00
	s_movk_i32 s12, 0x23f
	global_load_lds_dwordx4 v[10:11], off
	v_lshl_add_u64 v[10:11], v[4:5], 0, 64
	s_add_i32 m0, s14, 0x15100
	v_lshl_add_u64 v[4:5], v[4:5], 0, s[10:11]
	global_load_lds_dwordx4 v[10:11], off
	s_add_i32 m0, s14, 0x15500
	v_cmp_lt_i32_e64 s[34:35], s12, v158
	global_load_lds_dwordx4 v[4:5], off
	s_movk_i32 s12, 0x240
	v_cmp_gt_i32_e32 vcc, s12, v158
	v_sub_u32_e32 v166, 0x5f, v158
	s_and_saveexec_b64 s[22:23], vcc
	s_cbranch_execz .LBB0_311
	v_sub_u32_e32 v0, 0x5f, v158
	v_lshl_add_u32 v9, v158, 2, s1
	s_mov_b64 s[24:25], 0
	v_mov_b32_e32 v2, v158
	s_branch .LBB0_308
